# final LayerNorm phase: gamma/beta hoisted out of the row loop, next row prefetched during the reductions, per-chunk load/store waits removed
# speedup vs baseline: 1.0296x; 1.0039x over previous
; __device__ __forceinline__ int cur_lane() { int l; asm volatile("v_mbcnt_lo_u32_b32 %0, -1, 0\n\tv_mbcnt_hi_u32_b32 %0, -1, %0" : "=v"(l)); return l; }
; __device__ __forceinline__ void ln_row_h(const bf16* hrow, const float* g, const float* bta, float* orow, int lane) {
;     asm volatile("" : "+v"(lane));
;     typedef _Float16 h4 __attribute__((ext_vector_type(4)));
;     f32x4 v[4]; float s = 0.f;
; #pragma unroll
;     for (int j = 0; j < 4; ++j) { const h4 h = *((const h4*)hrow + lane + 64 * j); v[j] = (f32x4){(float)h[0], (float)h[1], (float)h[2], (float)h[3]}; s += (v[j][0] + v[j][1]) + (v[j][2] + v[j][3]); }
;     const float mean = wave_sum(s) * (1.f / D); float s2 = 0.f;
; #pragma unroll
;     for (int j = 0; j < 4; ++j) { v[j] = v[j] - mean; s2 += (v[j][0] * v[j][0] + v[j][1] * v[j][1]) + (v[j][2] * v[j][2] + v[j][3] * v[j][3]); }
;     const float rstd = 1.0f / sqrtf(wave_sum(s2) * (1.f / D) + 1e-5f);
; #pragma unroll
;     for (int j = 0; j < 4; ++j) { const f32x4 gg = *((const f32x4*)g + lane + 64 * j), bb = *((const f32x4*)bta + lane + 64 * j);
;         *((f32x4*)orow + lane + 64 * j) = v[j] * rstd * gg + bb; }
; __global__ void __launch_bounds__(NWAVES * 64, 2) fwd_megakernel(Args args) {
;     ...
;     for (int m = gw; m < M; m += NGW) ln_row_h(XB + (size_t)m * D, args.in[11] + (size_t)11 * D, args.in[12] + (size_t)11 * D, out + (size_t)m * D, cur_lane());
.LBB0_1297:
	v_readlane_b32 s16, v253, 6
	s_cmp_gt_i32 s16, 0xffff
	v_readlane_b32 s18, v253, 4
	v_readlane_b32 s17, v253, 7
	v_readlane_b32 s19, v253, 5
	s_cbranch_scc1 .LBB0_1300
	v_readlane_b32 s0, v253, 16
	v_readlane_b32 s1, v253, 17
	s_load_dwordx4 s[4:7], s[0:1], 0x58
	v_readlane_b32 s12, v254, 50
	v_readlane_b32 s14, v254, 52
	v_xor_b32_e32 v0, 1, v252
	v_readlane_b32 s15, v254, 53
	s_waitcnt lgkmcnt(0)
	s_add_u32 s2, s4, 0xb000
	s_addc_u32 s3, s5, 0
	s_add_u32 s4, s6, 0xb000
	s_addc_u32 s5, s7, 0
	s_ashr_i32 s17, s16, 31
	s_lshl_b64 s[0:1], s[16:17], 11
	s_add_u32 s0, s14, s0
	v_cmp_lt_i32_e32 vcc, v0, v209
	v_xor_b32_e32 v1, 2, v252
	s_addc_u32 s1, s15, s1
	v_cndmask_b32_e32 v0, v252, v0, vcc
	v_cmp_lt_i32_e32 vcc, v1, v209
	v_xor_b32_e32 v2, 4, v252
	s_add_u32 s6, s0, 0xb000000
	v_cndmask_b32_e32 v1, v252, v1, vcc
	v_cmp_lt_i32_e32 vcc, v2, v209
	v_xor_b32_e32 v3, 8, v252
	s_addc_u32 s7, s1, 0
	s_ashr_i32 s19, s18, 31
	v_cndmask_b32_e32 v2, v252, v2, vcc
	v_cmp_lt_i32_e32 vcc, v3, v209
	s_lshl_b64 s[8:9], s[18:19], 11
	s_lshl_b64 s[0:1], s[16:17], 12
	v_cndmask_b32_e32 v3, v252, v3, vcc
	v_readlane_b32 s13, v254, 51
	s_add_u32 s10, s12, s0
	v_lshlrev_b32_e32 v0, 2, v0
	v_lshlrev_b32_e32 v1, 2, v1
	v_lshlrev_b32_e32 v2, 2, v2
	v_lshlrev_b32_e32 v3, 2, v3
	s_addc_u32 s11, s13, s1
	s_lshl_b64 s[12:13], s[18:19], 12
	s_mov_b32 s14, 0xba800000
	v_mov_b32_e32 v4, 0x3727c5ac
	s_mov_b32 s15, 0xf800000
	v_mov_b32_e32 v5, 0x260
	v_mbcnt_lo_u32_b32 v50, -1, 0
	v_mbcnt_hi_u32_b32 v50, -1, v50
	v_lshlrev_b32_e32 v51, 3, v50
	v_lshlrev_b32_e32 v52, 4, v50
	v_mov_b32_e32 v53, 0
	global_load_dwordx2 v[60:61], v51, s[6:7]
	global_load_dwordx2 v[62:63], v51, s[6:7] offset:512
	global_load_dwordx2 v[64:65], v51, s[6:7] offset:1024
	global_load_dwordx2 v[66:67], v51, s[6:7] offset:1536
	global_load_dwordx4 v[100:103], v52, s[2:3]
	global_load_dwordx4 v[104:107], v52, s[2:3] offset:1024
	global_load_dwordx4 v[108:111], v52, s[2:3] offset:2048
	global_load_dwordx4 v[112:115], v52, s[2:3] offset:3072
	global_load_dwordx4 v[116:119], v52, s[4:5]
	global_load_dwordx4 v[120:123], v52, s[4:5] offset:1024
	global_load_dwordx4 v[124:127], v52, s[4:5] offset:2048
	global_load_dwordx4 v[128:131], v52, s[4:5] offset:3072
	s_waitcnt vmcnt(0)
	s_branch .Lln_body
.LBB0_1299:
	s_waitcnt vmcnt(4)
.Lln_body:
	v_mov_b32_e32 v14, v60
	v_mov_b32_e32 v15, v61
	v_mov_b32_e32 v16, v62
	v_mov_b32_e32 v17, v63
	v_mov_b32_e32 v18, v64
	v_mov_b32_e32 v19, v65
	v_mov_b32_e32 v20, v66
	v_mov_b32_e32 v21, v67
	s_add_i32 s16, s16, s18
	v_lshl_add_u64 v[26:27], s[10:11], 0, v[52:53]
	s_add_u32 s6, s6, s8
	s_addc_u32 s7, s7, s9
	s_add_u32 s10, s10, s12
	s_addc_u32 s11, s11, s13
	s_cmp_gt_i32 s16, 0xffff
	s_cbranch_scc1 .Lln_nopf
	global_load_dwordx2 v[60:61], v51, s[6:7]
	global_load_dwordx2 v[62:63], v51, s[6:7] offset:512
	global_load_dwordx2 v[64:65], v51, s[6:7] offset:1024
	global_load_dwordx2 v[66:67], v51, s[6:7] offset:1536
; __device__ __forceinline__ void ln_row_h(const bf16* hrow, const float* g, const float* bta, float* orow, int lane) {
;     ...
;     for (int j = 0; j < 4; ++j) { const h4 h = *((const h4*)hrow + lane + 64 * j); v[j] = (f32x4){(float)h[0], (float)h[1], (float)h[2], (float)h[3]}; s += (v[j][0] + v[j][1]) + (v[j][2] + v[j][3]); }
;     const float mean = wave_sum(s) * (1.f / D); float s2 = 0.f;
; #pragma unroll
;     for (int j = 0; j < 4; ++j) { v[j] = v[j] - mean; s2 += (v[j][0] * v[j][0] + v[j][1] * v[j][1]) + (v[j][2] * v[j][2] + v[j][3] * v[j][3]); }
;     const float rstd = 1.0f / sqrtf(wave_sum(s2) * (1.f / D) + 1e-5f);
; #pragma unroll
;     for (int j = 0; j < 4; ++j) { const f32x4 gg = *((const f32x4*)g + lane + 64 * j), bb = *((const f32x4*)bta + lane + 64 * j);
;         *((f32x4*)orow + lane + 64 * j) = v[j] * rstd * gg + bb; }
.Lln_nopf:
	v_cvt_f32_f16_e32 v28, v14
	v_cvt_f32_f16_sdwa v30, v14 dst_sel:DWORD dst_unused:UNUSED_PAD src0_sel:WORD_1
	v_cvt_f32_f16_e32 v29, v15
	v_cvt_f32_f16_sdwa v31, v15 dst_sel:DWORD dst_unused:UNUSED_PAD src0_sel:WORD_1
	v_cvt_f32_f16_e32 v32, v16
	v_cvt_f32_f16_sdwa v34, v16 dst_sel:DWORD dst_unused:UNUSED_PAD src0_sel:WORD_1
	v_cvt_f32_f16_e32 v33, v17
	v_cvt_f32_f16_sdwa v35, v17 dst_sel:DWORD dst_unused:UNUSED_PAD src0_sel:WORD_1
	v_pk_add_f32 v[28:29], v[28:29], v[30:31]
	v_cvt_f32_f16_e32 v36, v18
	v_cvt_f32_f16_sdwa v38, v18 dst_sel:DWORD dst_unused:UNUSED_PAD src0_sel:WORD_1
	v_pk_add_f32 v[30:31], v[32:33], v[34:35]
	v_cvt_f32_f16_e32 v40, v19
	v_cvt_f32_f16_sdwa v42, v19 dst_sel:DWORD dst_unused:UNUSED_PAD src0_sel:WORD_1
	v_add_f32_e32 v32, v28, v29
	v_pk_add_f32 v[28:29], v[30:31], v[30:31] op_sel:[0,1] op_sel_hi:[1,0]
	v_cvt_f32_f16_e32 v37, v20
	v_cvt_f32_f16_e32 v39, v21
	v_cvt_f32_f16_sdwa v41, v21 dst_sel:DWORD dst_unused:UNUSED_PAD src0_sel:WORD_1
	v_cvt_f32_f16_sdwa v29, v20 dst_sel:DWORD dst_unused:UNUSED_PAD src0_sel:WORD_1
	v_add_f32_e32 v38, v38, v36
	v_add_f32_e32 v40, v42, v40
	v_add_f32_e32 v36, 0, v32
	v_pk_add_f32 v[30:31], v[38:39], v[40:41]
	v_pk_add_f32 v[28:29], v[36:37], v[28:29]
	s_nop 0
	v_pk_add_f32 v[28:29], v[28:29], v[30:31]
	s_nop 0
	v_add_f32_e32 v28, v28, v29
	ds_bpermute_b32 v29, v0, v28
	s_waitcnt lgkmcnt(0)
	v_add_f32_e32 v28, v28, v29
	ds_bpermute_b32 v29, v1, v28
	s_waitcnt lgkmcnt(0)
	v_add_f32_e32 v28, v28, v29
	ds_bpermute_b32 v29, v2, v28
	s_waitcnt lgkmcnt(0)
	v_add_f32_e32 v28, v28, v29
	ds_bpermute_b32 v29, v3, v28
	s_waitcnt lgkmcnt(0)
	v_add_f32_e32 v28, v28, v29
	ds_bpermute_b32 v29, v207, v28
	s_waitcnt lgkmcnt(0)
	v_add_f32_e32 v28, v28, v29
	ds_bpermute_b32 v29, v208, v28
	s_waitcnt lgkmcnt(0)
	v_add_f32_e32 v36, v28, v29
	v_fma_mix_f32 v29, v36, s14, v14 op_sel:[0,0,1] op_sel_hi:[0,0,1]
	v_fma_mix_f32 v28, v36, s14, v14 op_sel_hi:[0,0,1]
	v_fma_mix_f32 v31, v36, s14, v15 op_sel:[0,0,1] op_sel_hi:[0,0,1]
	v_fma_mix_f32 v30, v36, s14, v15 op_sel_hi:[0,0,1]
	v_fma_mix_f32 v15, v36, s14, v16 op_sel:[0,0,1] op_sel_hi:[0,0,1]
	v_fma_mix_f32 v14, v36, s14, v16 op_sel_hi:[0,0,1]
	v_fma_mix_f32 v33, v36, s14, v17 op_sel:[0,0,1] op_sel_hi:[0,0,1]
	v_fma_mix_f32 v32, v36, s14, v17 op_sel_hi:[0,0,1]
	v_fma_mix_f32 v17, v36, s14, v18 op_sel:[0,0,1] op_sel_hi:[0,0,1]
	v_fma_mix_f32 v16, v36, s14, v18 op_sel_hi:[0,0,1]
	v_fma_mix_f32 v35, v36, s14, v19 op_sel:[0,0,1] op_sel_hi:[0,0,1]
	v_fma_mix_f32 v34, v36, s14, v19 op_sel_hi:[0,0,1]
	v_fma_mix_f32 v19, v36, s14, v21 op_sel:[0,0,1] op_sel_hi:[0,0,1]
	v_fma_mix_f32 v18, v36, s14, v21 op_sel_hi:[0,0,1]
	v_fma_mix_f32 v21, v36, s14, v20 op_sel:[0,0,1] op_sel_hi:[0,0,1]
	v_fma_mix_f32 v20, v36, s14, v20 op_sel_hi:[0,0,1]
	v_pk_mul_f32 v[36:37], v[30:31], v[30:31]
	v_pk_mul_f32 v[38:39], v[28:29], v[28:29]
	v_pk_mul_f32 v[40:41], v[32:33], v[32:33]
	v_pk_mul_f32 v[42:43], v[14:15], v[14:15]
	v_pk_mov_b32 v[48:49], v[38:39], v[36:37] op_sel:[1,0]
	v_mov_b32_e32 v39, v37
	v_pk_mov_b32 v[36:37], v[42:43], v[40:41] op_sel:[1,0]
	v_mov_b32_e32 v43, v41
	v_mul_f32_e32 v44, v16, v16
	v_mul_f32_e32 v46, v34, v34
	v_pk_add_f32 v[38:39], v[48:49], v[38:39]
	v_pk_add_f32 v[36:37], v[36:37], v[42:43]
	v_pk_fma_f32 v[40:41], v[16:17], v[16:17], v[44:45] op_sel_hi:[1,1,0]
	v_pk_fma_f32 v[44:45], v[34:35], v[34:35], v[46:47] op_sel_hi:[1,1,0]
	v_pk_add_f32 v[38:39], v[38:39], v[38:39] op_sel_hi:[0,1]
	v_pk_add_f32 v[36:37], v[36:37], v[36:37] op_sel_hi:[0,1]
	v_mul_f32_e32 v40, v20, v20
	v_mul_f32_e32 v44, v21, v21
	v_mul_f32_e32 v38, v18, v18
	v_mul_f32_e32 v36, v19, v19
	v_pk_add_f32 v[40:41], v[40:41], v[44:45]
	v_pk_add_f32 v[36:37], v[38:39], v[36:37]
	s_nop 0
	v_pk_add_f32 v[36:37], v[40:41], v[36:37]
	s_nop 0
	v_add_f32_e32 v36, v36, v37
	ds_bpermute_b32 v37, v0, v36
	s_waitcnt lgkmcnt(0)
	v_add_f32_e32 v36, v36, v37
	ds_bpermute_b32 v37, v1, v36
	s_waitcnt lgkmcnt(0)
	v_add_f32_e32 v36, v36, v37
	ds_bpermute_b32 v37, v2, v36
	s_waitcnt lgkmcnt(0)
	v_add_f32_e32 v36, v36, v37
	ds_bpermute_b32 v37, v3, v36
	s_waitcnt lgkmcnt(0)
	v_add_f32_e32 v36, v36, v37
	ds_bpermute_b32 v37, v207, v36
	s_waitcnt lgkmcnt(0)
	v_add_f32_e32 v36, v36, v37
	ds_bpermute_b32 v37, v208, v36
	s_waitcnt lgkmcnt(0)
	v_add_f32_e32 v36, v36, v37
	v_fmamk_f32 v36, v36, 0x3a800000, v4
	v_mul_f32_e32 v37, 0x4f800000, v36
	v_cmp_gt_f32_e32 vcc, s15, v36
	s_nop 1
	v_cndmask_b32_e32 v36, v36, v37, vcc
	v_sqrt_f32_e32 v37, v36
	s_nop 0
	v_add_u32_e32 v38, -1, v37
	v_add_u32_e32 v39, 1, v37
	v_fma_f32 v40, -v38, v37, v36
	v_fma_f32 v41, -v39, v37, v36
	v_cmp_ge_f32_e64 s[0:1], 0, v40
	s_nop 1
	v_cndmask_b32_e64 v37, v37, v38, s[0:1]
	v_cmp_lt_f32_e64 s[0:1], 0, v41
	s_nop 1
	v_cndmask_b32_e64 v37, v37, v39, s[0:1]
	v_mul_f32_e32 v38, 0x37800000, v37
	v_cndmask_b32_e32 v37, v37, v38, vcc
	v_cmp_class_f32_e32 vcc, v36, v5
	s_nop 1
	v_cndmask_b32_e32 v36, v37, v36, vcc
	v_div_scale_f32 v37, s[0:1], v36, v36, 1.0
	v_rcp_f32_e32 v39, v37
	v_div_scale_f32 v38, vcc, 1.0, v36, 1.0
	v_fma_f32 v40, -v37, v39, 1.0
	v_fmac_f32_e32 v39, v40, v39
	v_mul_f32_e32 v40, v38, v39
	v_fma_f32 v41, -v37, v40, v38
	v_fmac_f32_e32 v40, v41, v39
	v_fma_f32 v37, -v37, v40, v38
	v_div_fmas_f32 v37, v37, v39, v40
	v_div_fixup_f32 v36, v37, v36, 1.0
	v_pk_mul_f32 v[28:29], v[28:29], v[36:37] op_sel_hi:[1,0]
	v_pk_mul_f32 v[30:31], v[30:31], v[36:37] op_sel_hi:[1,0]
	v_pk_fma_f32 v[6:7], v[100:101], v[28:29], v[116:117]
	v_pk_fma_f32 v[8:9], v[102:103], v[30:31], v[118:119]
	global_store_dwordx4 v[26:27], v[6:9], off
	v_pk_mul_f32 v[28:29], v[32:33], v[36:37] op_sel_hi:[1,0]
	v_pk_mul_f32 v[14:15], v[14:15], v[36:37] op_sel_hi:[1,0]
	v_pk_mul_f32 v[16:17], v[16:17], v[36:37] op_sel_hi:[1,0]
	v_pk_fma_f32 v[68:69], v[104:105], v[14:15], v[120:121]
	v_pk_fma_f32 v[70:71], v[106:107], v[28:29], v[122:123]
	global_store_dwordx4 v[26:27], v[68:71], off offset:1024
	v_pk_mul_f32 v[14:15], v[34:35], v[36:37] op_sel_hi:[1,0]
	v_pk_fma_f32 v[72:73], v[108:109], v[16:17], v[124:125]
	v_pk_fma_f32 v[74:75], v[110:111], v[14:15], v[126:127]
	global_store_dwordx4 v[26:27], v[72:75], off offset:2048
	v_pk_mul_f32 v[14:15], v[18:19], v[36:37] op_sel_hi:[1,0]
	v_pk_mul_f32 v[16:17], v[20:21], v[36:37] op_sel_hi:[1,0]
	v_pk_fma_f32 v[78:79], v[114:115], v[14:15], v[130:131]
	v_pk_fma_f32 v[76:77], v[112:113], v[16:17], v[128:129]
	global_store_dwordx4 v[26:27], v[76:79], off offset:3072
	s_cbranch_scc0 .LBB0_1299
